# S1 plus attention epilogue: 16 dwordx2 stores per lane widened to 8 dwordx4 via v_permlane32_swap (bit-identical bytes)
# speedup vs baseline: 1.0038x; 1.0038x over previous
; __device__ __forceinline__ unsigned cvt_pk_bf16(float lo, float hi) { unsigned r; asm volatile("v_cvt_pk_bf16_f32 %0, %1, %2" : "=v"(r) : "v"(lo), "v"(hi)); return r; }
; __device__ __forceinline__ float bf_lo(unsigned w) { return __uint_as_float(w << 16); }
; __device__ __forceinline__ float bf_hi(unsigned w) { return __uint_as_float(w & 0xffff0000u); }
; #define ATT_LOADK(t) do { rk0 = *(const u32x4*)(gk + (size_t)(64 * (t)) * NKN); rk1 = *(const u32x4*)(gk + (size_t)(64 * (t) + 32) * NKN); rr = *(const u32x4*)(gr + (size_t)(64 * (t)) * 64); } while (0)
; #define ATT_LOADV(t) do { rv0 = *(const u32x4*)(gv + 64 * (t)); rv1 = *(const u32x4*)(gv + (size_t)64 * M + 64 * (t)); } while (0)
; #define ATT_STOREK(ko) do { *(LAS u32x4*)(lds + (ko) + lk) = rk0; *(LAS u32x4*)(lds + (ko) + lk + 32 * KROW) = rk1; *(LAS u32x4*)(lds + (ko) + lr) = rr; } while (0)
; __device__ __forceinline__ void unit(LAS unsigned char* lds, int b, int h, int qb, const bf16_t* Q, const bf16_t* Kn, const bf16_t* Kr, const bf16_t* VT, const bf16_t* proj, bf16_t* ymix, int wv) {
;     ...
;     ATT_LOADK(0); ATT_LOADV(0); ATT_STOREK(0); ATT_STOREV(0);
;     ATT_LOADK(1); ATT_STOREK(KBUF);
;     __syncthreads();
; #pragma unroll
;     for (int ks = 0; ks < 12; ++ks) asm volatile("" : "+v"(qf[ks]));
;     int k0 = 0, k1 = KBUF, k2 = 2 * KBUF, v0 = 0, v1 = VBUF;
;     ...
;     lrun += shfl_xor_f(lrun, 32);
;     const float inv = 1.f / lrun;
;     const size_t tok = (size_t)tok0 + qidx;
;     u32x2 gts[4][4];
; #pragma unroll
;     for (int blk = 0; blk < 4; ++blk)
; #pragma unroll
;         for (int g = 0; g < 4; ++g) gts[blk][g] = *(const u32x2*)(proj + tok * NIN + PJ_BG + h * 128 + 32 * blk + 8 * g + 4 * hi);
; #pragma unroll
;     for (int blk = 0; blk < 4; ++blk)
; #pragma unroll
;         for (int g = 0; g < 4; ++g) { const int dv = 32 * blk + 8 * g + 4 * hi; const u32x2 gt = gts[blk][g];
;             u32x2 w; w.x = cvt_pk_bf16(o[blk][4 * g + 0] * inv * bf_lo(gt.x), o[blk][4 * g + 1] * inv * bf_hi(gt.x)); w.y = cvt_pk_bf16(o[blk][4 * g + 2] * inv * bf_lo(gt.y), o[blk][4 * g + 3] * inv * bf_hi(gt.y));
;             *(u32x2*)(ymix + tok * DM + 512 + h * 128 + dv) = w; }
.LBB0_605:
	s_add_i32 s8, s71, 0
	s_add_i32 s8, s8, 0x12c00
	v_add3_u32 v0, s8, v227, v226
	ds_read2_b64 v[2:5], v0 offset1:2
	v_ashrrev_i32_e32 v217, 31, v216
	v_mov_b64_e32 v[6:7], s[22:23]
	v_lshl_add_u64 v[120:121], v[216:217], 0, s[54:55]
	v_mad_u64_u32 v[122:123], s[8:9], v120, s66, v[6:7]
	ds_read2_b64 v[6:9], v0 offset0:4 offset1:6
	ds_read2_b64 v[12:15], v0 offset0:8 offset1:10
	v_add_u32_e32 v88, 0x1000, v0
	v_add_u32_e32 v104, 0x2000, v0
	s_waitcnt lgkmcnt(2)
	v_mfma_f32_32x32x16_bf16 v[64:79], v[2:5], v[200:203], v[64:79]
	ds_read2_b64 v[2:5], v0 offset0:12 offset1:14
	v_add_u32_e32 v0, 0x3000, v0
	v_mad_i32_i24 v123, v121, s66, v123
	s_lshl_b32 s12, s69, 1
	ds_read2_b64 v[80:83], v88 offset0:32 offset1:34
	ds_read2_b64 v[84:87], v88 offset0:36 offset1:38
	v_mov_b32_e32 v11, v222
	s_add_i32 s68, s68, s31
	s_waitcnt lgkmcnt(4)
	v_mfma_f32_32x32x16_bf16 v[64:79], v[6:9], v[196:199], v[64:79]
	ds_read2_b64 v[6:9], v88 offset0:40 offset1:42
	ds_read2_b64 v[88:91], v88 offset0:44 offset1:46
	ds_read2_b64 v[92:95], v104 offset0:64 offset1:66
	ds_read2_b64 v[96:99], v104 offset0:68 offset1:70
	ds_read2_b64 v[100:103], v104 offset0:72 offset1:74
	ds_read2_b64 v[104:107], v104 offset0:76 offset1:78
	ds_read2_b64 v[108:111], v0 offset0:96 offset1:98
	s_cmpk_lt_i32 s68, 0x400
	s_waitcnt lgkmcnt(10)
	v_mfma_f32_32x32x16_bf16 v[64:79], v[12:15], v[192:195], v[64:79]
	ds_read2_b64 v[12:15], v0 offset0:100 offset1:102
	ds_read2_b64 v[112:115], v0 offset0:104 offset1:106
	ds_read2_b64 v[116:119], v0 offset0:108 offset1:110
	v_lshlrev_b32_e32 v0, 1, v225
	s_waitcnt lgkmcnt(0)
	s_barrier
	v_mfma_f32_32x32x16_bf16 v[64:79], v[2:5], v[180:183], v[64:79]
	v_lshl_add_u64 v[2:3], v[122:123], 0, s[12:13]
	v_lshl_add_u64 v[2:3], v[2:3], 0, v[0:1]
	v_add_co_u32_e32 v4, vcc, s67, v2
	s_nop 1
	v_addc_co_u32_e32 v5, vcc, 0, v3, vcc
	global_load_dwordx2 v[122:123], v[4:5], off
	v_lshl_add_u64 v[2:3], v[2:3], 0, s[16:17]
	v_mfma_f32_32x32x16_bf16 v[48:63], v[80:83], v[200:203], v[48:63]
	global_load_dwordx2 v[80:81], v[2:3], off offset:16
	global_load_dwordx2 v[82:83], v[2:3], off offset:32
	v_lshlrev_b32_e32 v4, 2, v11
	v_xor_b32_e32 v4, 0x80, v4
	ds_bpermute_b32 v4, v4, v10
	v_mfma_f32_32x32x16_bf16 v[48:63], v[84:87], v[196:199], v[48:63]
	v_mfma_f32_32x32x16_bf16 v[48:63], v[6:9], v[192:195], v[48:63]
	s_waitcnt lgkmcnt(0)
	v_add_f32_e32 v6, v10, v4
	global_load_dwordx2 v[10:11], v[2:3], off offset:48
	global_load_dwordx2 v[84:85], v[2:3], off offset:64
	global_load_dwordx2 v[86:87], v[2:3], off offset:80
	global_load_dwordx2 v[124:125], v[2:3], off offset:96
	global_load_dwordx2 v[126:127], v[2:3], off offset:112
	global_load_dwordx2 v[128:129], v[2:3], off offset:128
	v_div_scale_f32 v7, s[8:9], v6, v6, 1.0
	v_rcp_f32_e32 v134, v7
	v_mfma_f32_32x32x16_bf16 v[48:63], v[88:91], v[180:183], v[48:63]
	global_load_dwordx2 v[88:89], v[2:3], off offset:144
	global_load_dwordx2 v[90:91], v[2:3], off offset:160
	global_load_dwordx2 v[130:131], v[2:3], off offset:176
	global_load_dwordx2 v[132:133], v[2:3], off offset:192
	global_load_dwordx2 v[8:9], v[2:3], off offset:208
	global_load_dwordx2 v[4:5], v[2:3], off offset:224
	s_nop 0
	global_load_dwordx2 v[2:3], v[2:3], off offset:240
	v_mfma_f32_32x32x16_bf16 v[32:47], v[92:95], v[200:203], v[32:47]
	v_fma_f32 v92, -v7, v134, 1.0
	v_fmac_f32_e32 v134, v92, v134
	v_div_scale_f32 v92, vcc, 1.0, v6, 1.0
	v_mul_f32_e32 v93, v92, v134
	v_fma_f32 v94, -v7, v93, v92
	v_fmac_f32_e32 v93, v94, v134
	v_fma_f32 v7, -v7, v93, v92
	v_mfma_f32_32x32x16_bf16 v[16:31], v[108:111], v[200:203], v[16:31]
	v_div_fmas_f32 v7, v7, v134, v93
	v_div_fixup_f32 v92, v7, v6, 1.0
	v_mul_f32_e32 v64, v64, v92
	v_lshlrev_b64 v[6:7], 12, v[120:121]
	v_mul_f32_e32 v65, v65, v92
	v_lshl_add_u64 v[6:7], s[46:47], 0, v[6:7]
	v_lshl_add_u64 v[6:7], v[6:7], 0, s[12:13]
	v_lshl_add_u64 v[6:7], v[6:7], 0, v[0:1]
	v_mul_f32_e32 v0, v68, v92
	v_mfma_f32_32x32x16_bf16 v[16:31], v[12:15], v[196:199], v[16:31]
	v_mul_f32_e32 v12, v69, v92
	s_waitcnt vmcnt(15)
	v_lshlrev_b32_e32 v93, 16, v122
	v_mul_f32_e32 v64, v64, v93
	v_and_b32_e32 v93, 0xffff0000, v122
	v_mul_f32_e32 v65, v65, v93
	v_cvt_pk_bf16_f32 v244, v64, v65
	v_mul_f32_e32 v65, v66, v92
	v_lshlrev_b32_e32 v66, 16, v123
	v_mul_f32_e32 v65, v65, v66
	v_mul_f32_e32 v66, v67, v92
	v_and_b32_e32 v67, 0xffff0000, v123
	v_mul_f32_e32 v66, v66, v67
	v_cvt_pk_bf16_f32 v245, v65, v66
	v_and_b32_e32 v252, 32, v222
	v_lshrrev_b32_e32 v252, 2, v252
	v_mov_b32_e32 v253, 0
	v_lshl_add_u64 v[252:253], v[6:7], 0, v[252:253]
	s_waitcnt vmcnt(14)
	v_lshlrev_b32_e32 v64, 16, v80
	v_and_b32_e32 v13, 0xffff0000, v80
	v_mul_f32_e32 v0, v0, v64
	v_mul_f32_e32 v12, v12, v13
	v_cvt_pk_bf16_f32 v246, v0, v12
	v_mul_f32_e32 v0, v70, v92
	v_lshlrev_b32_e32 v13, 16, v81
	v_mul_f32_e32 v0, v0, v13
	v_mul_f32_e32 v13, v71, v92
	v_and_b32_e32 v14, 0xffff0000, v81
	v_mul_f32_e32 v13, v13, v14
	v_cvt_pk_bf16_f32 v247, v0, v13
	s_nop 1
	v_permlane32_swap_b32_e32 v244, v246
	v_permlane32_swap_b32_e32 v245, v247
	global_store_dwordx4 v[252:253], v[244:247], off offset:1024
	v_mul_f32_e32 v0, v72, v92
	s_waitcnt vmcnt(14)
	v_lshlrev_b32_e32 v12, 16, v82
	v_mul_f32_e32 v0, v0, v12
	v_mul_f32_e32 v12, v73, v92
	v_and_b32_e32 v13, 0xffff0000, v82
	v_mul_f32_e32 v12, v12, v13
	v_cvt_pk_bf16_f32 v248, v0, v12
	v_mul_f32_e32 v0, v74, v92
	v_lshlrev_b32_e32 v13, 16, v83
	v_mul_f32_e32 v0, v0, v13
	v_mul_f32_e32 v13, v75, v92
	v_and_b32_e32 v14, 0xffff0000, v83
	v_mul_f32_e32 v13, v13, v14
	v_cvt_pk_bf16_f32 v249, v0, v13
	v_mul_f32_e32 v0, v76, v92
	s_waitcnt vmcnt(13)
; __device__ __forceinline__ unsigned cvt_pk_bf16(float lo, float hi) { unsigned r; asm volatile("v_cvt_pk_bf16_f32 %0, %1, %2" : "=v"(r) : "v"(lo), "v"(hi)); return r; }
; __device__ __forceinline__ float bf_lo(unsigned w) { return __uint_as_float(w << 16); }
; __device__ __forceinline__ float bf_hi(unsigned w) { return __uint_as_float(w & 0xffff0000u); }
; __device__ __forceinline__ void unit(LAS unsigned char* lds, int b, int h, int qb, const bf16_t* Q, const bf16_t* Kn, const bf16_t* Kr, const bf16_t* VT, const bf16_t* proj, bf16_t* ymix, int wv) {
;     ...
;     u32x2 gts[4][4];
; #pragma unroll
;     for (int blk = 0; blk < 4; ++blk)
; #pragma unroll
;         for (int g = 0; g < 4; ++g) gts[blk][g] = *(const u32x2*)(proj + tok * NIN + PJ_BG + h * 128 + 32 * blk + 8 * g + 4 * hi);
; #pragma unroll
;     for (int blk = 0; blk < 4; ++blk)
; #pragma unroll
;         for (int g = 0; g < 4; ++g) { const int dv = 32 * blk + 8 * g + 4 * hi; const u32x2 gt = gts[blk][g];
;             u32x2 w; w.x = cvt_pk_bf16(o[blk][4 * g + 0] * inv * bf_lo(gt.x), o[blk][4 * g + 1] * inv * bf_hi(gt.x)); w.y = cvt_pk_bf16(o[blk][4 * g + 2] * inv * bf_lo(gt.y), o[blk][4 * g + 3] * inv * bf_hi(gt.y));
;             *(u32x2*)(ymix + tok * DM + 512 + h * 128 + dv) = w; }
	v_lshlrev_b32_e32 v12, 16, v10
	v_mul_f32_e32 v0, v0, v12
	v_mul_f32_e32 v12, v77, v92
	v_and_b32_e32 v10, 0xffff0000, v10
	v_mul_f32_e32 v10, v12, v10
	v_cvt_pk_bf16_f32 v250, v0, v10
	v_mul_f32_e32 v0, v78, v92
	v_lshlrev_b32_e32 v12, 16, v11
	v_mul_f32_e32 v0, v0, v12
	v_mul_f32_e32 v12, v79, v92
	v_and_b32_e32 v11, 0xffff0000, v11
	v_mul_f32_e32 v11, v12, v11
	v_mfma_f32_32x32x16_bf16 v[32:47], v[96:99], v[196:199], v[32:47]
	v_cvt_pk_bf16_f32 v251, v0, v11
	s_nop 1
	v_permlane32_swap_b32_e32 v248, v250
	v_permlane32_swap_b32_e32 v249, v251
	global_store_dwordx4 v[252:253], v[248:251], off offset:1056
	v_mul_f32_e32 v0, v48, v92
	s_waitcnt vmcnt(13)
	v_lshlrev_b32_e32 v10, 16, v84
	v_mul_f32_e32 v0, v0, v10
	v_mul_f32_e32 v10, v49, v92
	v_and_b32_e32 v11, 0xffff0000, v84
	v_mul_f32_e32 v10, v10, v11
	v_cvt_pk_bf16_f32 v244, v0, v10
	v_mul_f32_e32 v0, v50, v92
	v_lshlrev_b32_e32 v11, 16, v85
	v_mul_f32_e32 v0, v0, v11
	v_mul_f32_e32 v11, v51, v92
	v_and_b32_e32 v12, 0xffff0000, v85
	v_mul_f32_e32 v11, v11, v12
	v_cvt_pk_bf16_f32 v245, v0, v11
	v_mul_f32_e32 v0, v52, v92
	s_waitcnt vmcnt(12)
	v_lshlrev_b32_e32 v10, 16, v86
	v_mul_f32_e32 v0, v0, v10
	v_mul_f32_e32 v10, v53, v92
	v_and_b32_e32 v11, 0xffff0000, v86
	v_mfma_f32_32x32x16_bf16 v[32:47], v[100:103], v[192:195], v[32:47]
	v_mul_f32_e32 v10, v10, v11
	v_cvt_pk_bf16_f32 v246, v0, v10
	v_mul_f32_e32 v0, v54, v92
	v_lshlrev_b32_e32 v11, 16, v87
	v_mul_f32_e32 v0, v0, v11
	v_mul_f32_e32 v11, v55, v92
	v_and_b32_e32 v12, 0xffff0000, v87
	v_mul_f32_e32 v11, v11, v12
	v_cvt_pk_bf16_f32 v247, v0, v11
	s_nop 1
	v_permlane32_swap_b32_e32 v244, v246
	v_permlane32_swap_b32_e32 v245, v247
	global_store_dwordx4 v[252:253], v[244:247], off offset:1088
	v_mul_f32_e32 v0, v56, v92
	s_waitcnt vmcnt(12)
	v_lshlrev_b32_e32 v10, 16, v124
	v_mul_f32_e32 v0, v0, v10
	v_mul_f32_e32 v10, v57, v92
	v_and_b32_e32 v11, 0xffff0000, v124
	v_mul_f32_e32 v10, v10, v11
	v_cvt_pk_bf16_f32 v248, v0, v10
	v_mul_f32_e32 v0, v58, v92
	v_lshlrev_b32_e32 v11, 16, v125
	v_mfma_f32_32x32x16_bf16 v[32:47], v[104:107], v[180:183], v[32:47]
	v_mul_f32_e32 v0, v0, v11
	v_mul_f32_e32 v11, v59, v92
	v_and_b32_e32 v12, 0xffff0000, v125
	v_mul_f32_e32 v11, v11, v12
	v_cvt_pk_bf16_f32 v249, v0, v11
	v_mul_f32_e32 v0, v60, v92
	s_waitcnt vmcnt(11)
	v_lshlrev_b32_e32 v10, 16, v126
	v_mul_f32_e32 v0, v0, v10
	v_mul_f32_e32 v10, v61, v92
	v_and_b32_e32 v11, 0xffff0000, v126
	v_mul_f32_e32 v10, v10, v11
	v_cvt_pk_bf16_f32 v250, v0, v10
	v_mul_f32_e32 v0, v62, v92
	v_lshlrev_b32_e32 v11, 16, v127
	v_mul_f32_e32 v0, v0, v11
	v_mul_f32_e32 v11, v63, v92
	v_and_b32_e32 v12, 0xffff0000, v127
	v_mul_f32_e32 v11, v11, v12
	v_cvt_pk_bf16_f32 v251, v0, v11
	s_nop 1
	v_permlane32_swap_b32_e32 v248, v250
	v_permlane32_swap_b32_e32 v249, v251
	global_store_dwordx4 v[252:253], v[248:251], off offset:1120
	v_mul_f32_e32 v0, v32, v92
	s_waitcnt vmcnt(11)
	v_lshlrev_b32_e32 v10, 16, v128
	v_mul_f32_e32 v0, v0, v10
	v_mul_f32_e32 v10, v33, v92
	v_and_b32_e32 v11, 0xffff0000, v128
	v_mul_f32_e32 v10, v10, v11
	v_cvt_pk_bf16_f32 v244, v0, v10
	v_mul_f32_e32 v0, v34, v92
	v_lshlrev_b32_e32 v11, 16, v129
	v_mul_f32_e32 v0, v0, v11
	v_mul_f32_e32 v11, v35, v92
	v_and_b32_e32 v12, 0xffff0000, v129
	v_mul_f32_e32 v11, v11, v12
	v_cvt_pk_bf16_f32 v245, v0, v11
	v_mul_f32_e32 v0, v36, v92
	s_waitcnt vmcnt(10)
; __device__ __forceinline__ unsigned cvt_pk_bf16(float lo, float hi) { unsigned r; asm volatile("v_cvt_pk_bf16_f32 %0, %1, %2" : "=v"(r) : "v"(lo), "v"(hi)); return r; }
; __device__ __forceinline__ float bf_lo(unsigned w) { return __uint_as_float(w << 16); }
; __device__ __forceinline__ float bf_hi(unsigned w) { return __uint_as_float(w & 0xffff0000u); }
; __device__ __forceinline__ void unit(LAS unsigned char* lds, int b, int h, int qb, const bf16_t* Q, const bf16_t* Kn, const bf16_t* Kr, const bf16_t* VT, const bf16_t* proj, bf16_t* ymix, int wv) {
;     ...
;     u32x2 gts[4][4];
; #pragma unroll
;     for (int blk = 0; blk < 4; ++blk)
; #pragma unroll
;         for (int g = 0; g < 4; ++g) gts[blk][g] = *(const u32x2*)(proj + tok * NIN + PJ_BG + h * 128 + 32 * blk + 8 * g + 4 * hi);
; #pragma unroll
;     for (int blk = 0; blk < 4; ++blk)
; #pragma unroll
;         for (int g = 0; g < 4; ++g) { const int dv = 32 * blk + 8 * g + 4 * hi; const u32x2 gt = gts[blk][g];
;             u32x2 w; w.x = cvt_pk_bf16(o[blk][4 * g + 0] * inv * bf_lo(gt.x), o[blk][4 * g + 1] * inv * bf_hi(gt.x)); w.y = cvt_pk_bf16(o[blk][4 * g + 2] * inv * bf_lo(gt.y), o[blk][4 * g + 3] * inv * bf_hi(gt.y));
;             *(u32x2*)(ymix + tok * DM + 512 + h * 128 + dv) = w; }
	v_lshlrev_b32_e32 v10, 16, v88
	v_mul_f32_e32 v0, v0, v10
	v_mul_f32_e32 v10, v37, v92
	v_and_b32_e32 v11, 0xffff0000, v88
	v_mfma_f32_32x32x16_bf16 v[16:31], v[112:115], v[192:195], v[16:31]
	v_mul_f32_e32 v10, v10, v11
	v_cvt_pk_bf16_f32 v246, v0, v10
	v_mul_f32_e32 v0, v38, v92
	v_lshlrev_b32_e32 v11, 16, v89
	v_mul_f32_e32 v0, v0, v11
	v_mul_f32_e32 v11, v39, v92
	v_and_b32_e32 v12, 0xffff0000, v89
	v_mul_f32_e32 v11, v11, v12
	v_cvt_pk_bf16_f32 v247, v0, v11
	s_nop 1
	v_permlane32_swap_b32_e32 v244, v246
	v_permlane32_swap_b32_e32 v245, v247
	global_store_dwordx4 v[252:253], v[244:247], off offset:1152
	v_mul_f32_e32 v0, v40, v92
	s_waitcnt vmcnt(10)
	v_lshlrev_b32_e32 v10, 16, v90
	v_mul_f32_e32 v0, v0, v10
	v_mul_f32_e32 v10, v41, v92
	v_and_b32_e32 v11, 0xffff0000, v90
	v_mul_f32_e32 v10, v10, v11
	v_cvt_pk_bf16_f32 v248, v0, v10
	v_mul_f32_e32 v0, v42, v92
	v_lshlrev_b32_e32 v11, 16, v91
	v_mfma_f32_32x32x16_bf16 v[16:31], v[116:119], v[180:183], v[16:31]
	v_mul_f32_e32 v0, v0, v11
	v_mul_f32_e32 v11, v43, v92
	v_and_b32_e32 v12, 0xffff0000, v91
	v_mul_f32_e32 v11, v11, v12
	v_cvt_pk_bf16_f32 v249, v0, v11
	v_mul_f32_e32 v0, v44, v92
	s_waitcnt vmcnt(9)
	v_lshlrev_b32_e32 v10, 16, v130
	v_mul_f32_e32 v0, v0, v10
	v_mul_f32_e32 v10, v45, v92
	v_and_b32_e32 v11, 0xffff0000, v130
	v_mul_f32_e32 v10, v10, v11
	v_cvt_pk_bf16_f32 v250, v0, v10
	v_mul_f32_e32 v0, v46, v92
	v_lshlrev_b32_e32 v11, 16, v131
	v_mul_f32_e32 v0, v0, v11
	v_mul_f32_e32 v11, v47, v92
	v_and_b32_e32 v12, 0xffff0000, v131
	v_mul_f32_e32 v11, v11, v12
	v_cvt_pk_bf16_f32 v251, v0, v11
	s_nop 1
	v_permlane32_swap_b32_e32 v248, v250
	v_permlane32_swap_b32_e32 v249, v251
	global_store_dwordx4 v[252:253], v[248:251], off offset:1184
	v_mul_f32_e32 v0, v16, v92
	s_waitcnt vmcnt(9)
	v_lshlrev_b32_e32 v10, 16, v132
	v_mul_f32_e32 v0, v0, v10
	v_mul_f32_e32 v10, v17, v92
	v_and_b32_e32 v11, 0xffff0000, v132
	v_mul_f32_e32 v10, v10, v11
	v_cvt_pk_bf16_f32 v244, v0, v10
	v_mul_f32_e32 v0, v18, v92
	v_lshlrev_b32_e32 v11, 16, v133
	v_mul_f32_e32 v0, v0, v11
	v_mul_f32_e32 v11, v19, v92
	v_and_b32_e32 v12, 0xffff0000, v133
	v_mul_f32_e32 v11, v11, v12
	v_cvt_pk_bf16_f32 v245, v0, v11
	v_mul_f32_e32 v0, v20, v92
	s_waitcnt vmcnt(8)
	v_lshlrev_b32_e32 v10, 16, v8
	v_mul_f32_e32 v0, v0, v10
	v_mul_f32_e32 v10, v21, v92
	v_and_b32_e32 v8, 0xffff0000, v8
	v_mul_f32_e32 v8, v10, v8
	v_cvt_pk_bf16_f32 v246, v0, v8
	v_mul_f32_e32 v0, v22, v92
	v_lshlrev_b32_e32 v10, 16, v9
	v_mul_f32_e32 v0, v0, v10
	v_mul_f32_e32 v10, v23, v92
	v_and_b32_e32 v9, 0xffff0000, v9
	v_mul_f32_e32 v9, v10, v9
	v_cvt_pk_bf16_f32 v247, v0, v9
	s_nop 1
	v_permlane32_swap_b32_e32 v244, v246
	v_permlane32_swap_b32_e32 v245, v247
	global_store_dwordx4 v[252:253], v[244:247], off offset:1216
	v_mul_f32_e32 v0, v24, v92
	s_waitcnt vmcnt(8)
	v_lshlrev_b32_e32 v8, 16, v4
	v_mul_f32_e32 v0, v0, v8
	v_mul_f32_e32 v8, v25, v92
	v_and_b32_e32 v4, 0xffff0000, v4
	v_mul_f32_e32 v4, v8, v4
	v_cvt_pk_bf16_f32 v248, v0, v4
	v_mul_f32_e32 v0, v26, v92
	v_lshlrev_b32_e32 v8, 16, v5
	v_mul_f32_e32 v0, v0, v8
	v_mul_f32_e32 v8, v27, v92
	v_and_b32_e32 v5, 0xffff0000, v5
	v_mul_f32_e32 v5, v8, v5
	v_cvt_pk_bf16_f32 v249, v0, v5
	v_mul_f32_e32 v0, v28, v92
	s_waitcnt vmcnt(7)
	v_lshlrev_b32_e32 v4, 16, v2
	v_mul_f32_e32 v0, v0, v4
	v_mul_f32_e32 v4, v29, v92
	v_and_b32_e32 v2, 0xffff0000, v2
	v_mul_f32_e32 v2, v4, v2
	v_cvt_pk_bf16_f32 v250, v0, v2
	v_mul_f32_e32 v0, v30, v92
	v_lshlrev_b32_e32 v4, 16, v3
	v_mul_f32_e32 v0, v0, v4
	v_mul_f32_e32 v4, v31, v92
	v_and_b32_e32 v3, 0xffff0000, v3
	v_mul_f32_e32 v3, v4, v3
	v_cvt_pk_bf16_f32 v251, v0, v3
	s_nop 1
	v_permlane32_swap_b32_e32 v248, v250
	v_permlane32_swap_b32_e32 v249, v251
	global_store_dwordx4 v[252:253], v[248:251], off offset:1248
	s_cbranch_scc0 .LBB0_633

; __device__ __forceinline__ unsigned cvt_pk_bf16(float lo, float hi) { unsigned r; asm volatile("v_cvt_pk_bf16_f32 %0, %1, %2" : "=v"(r) : "v"(lo), "v"(hi)); return r; }
; __device__ __forceinline__ float bf_lo(unsigned w) { return __uint_as_float(w << 16); }
; __device__ __forceinline__ float bf_hi(unsigned w) { return __uint_as_float(w & 0xffff0000u); }
; #define ATT_LOADK(t) do { rk0 = *(const u32x4*)(gk + (size_t)(64 * (t)) * NKN); rk1 = *(const u32x4*)(gk + (size_t)(64 * (t) + 32) * NKN); rr = *(const u32x4*)(gr + (size_t)(64 * (t)) * 64); } while (0)
; #define ATT_LOADV(t) do { rv0 = *(const u32x4*)(gv + 64 * (t)); rv1 = *(const u32x4*)(gv + (size_t)64 * M + 64 * (t)); } while (0)
; #define ATT_STOREK(ko) do { *(LAS u32x4*)(lds + (ko) + lk) = rk0; *(LAS u32x4*)(lds + (ko) + lk + 32 * KROW) = rk1; *(LAS u32x4*)(lds + (ko) + lr) = rr; } while (0)
; __device__ __forceinline__ void unit(LAS unsigned char* lds, int b, int h, int qb, const bf16_t* Q, const bf16_t* Kn, const bf16_t* Kr, const bf16_t* VT, const bf16_t* proj, bf16_t* ymix, int wv) {
;     ...
;     ATT_LOADK(0); ATT_LOADV(0); ATT_STOREK(0); ATT_STOREV(0);
;     ATT_LOADK(1); ATT_STOREK(KBUF);
;     __syncthreads();
; #pragma unroll
;     for (int ks = 0; ks < 12; ++ks) asm volatile("" : "+v"(qf[ks]));
;     int k0 = 0, k1 = KBUF, k2 = 2 * KBUF, v0 = 0, v1 = VBUF;
;     ...
;     lrun += shfl_xor_f(lrun, 32);
;     const float inv = 1.f / lrun;
;     const size_t tok = (size_t)tok0 + qidx;
;     u32x2 gts[4][4];
; #pragma unroll
;     for (int blk = 0; blk < 4; ++blk)
; #pragma unroll
;         for (int g = 0; g < 4; ++g) gts[blk][g] = *(const u32x2*)(proj + tok * NIN + PJ_BG + h * 128 + 32 * blk + 8 * g + 4 * hi);
; #pragma unroll
;     for (int blk = 0; blk < 4; ++blk)
; #pragma unroll
;         for (int g = 0; g < 4; ++g) { const int dv = 32 * blk + 8 * g + 4 * hi; const u32x2 gt = gts[blk][g];
;             u32x2 w; w.x = cvt_pk_bf16(o[blk][4 * g + 0] * inv * bf_lo(gt.x), o[blk][4 * g + 1] * inv * bf_hi(gt.x)); w.y = cvt_pk_bf16(o[blk][4 * g + 2] * inv * bf_lo(gt.y), o[blk][4 * g + 3] * inv * bf_hi(gt.y));
;             *(u32x2*)(ymix + tok * DM + 512 + h * 128 + dv) = w; }
.LBB0_1170:
	s_add_i32 s6, s58, 0
	s_add_i32 s6, s6, 0x12c00
	v_add3_u32 v0, s6, v227, v226
	ds_read2_b64 v[2:5], v0 offset1:2
	v_ashrrev_i32_e32 v217, 31, v216
	v_mov_b64_e32 v[6:7], s[46:47]
	v_lshl_add_u64 v[120:121], v[216:217], 0, s[16:17]
	v_mad_u64_u32 v[122:123], s[16:17], v120, s54, v[6:7]
	ds_read2_b64 v[6:9], v0 offset0:4 offset1:6
	ds_read2_b64 v[12:15], v0 offset0:8 offset1:10
	v_add_u32_e32 v88, 0x1000, v0
	v_add_u32_e32 v104, 0x2000, v0
	s_waitcnt lgkmcnt(2)
	v_mfma_f32_32x32x16_bf16 v[64:79], v[2:5], v[200:203], v[64:79]
	ds_read2_b64 v[2:5], v0 offset0:12 offset1:14
	v_add_u32_e32 v0, 0x3000, v0
	v_mad_i32_i24 v123, v121, s54, v123
	s_lshl_b32 s6, s56, 1
	ds_read2_b64 v[80:83], v88 offset0:32 offset1:34
	ds_read2_b64 v[84:87], v88 offset0:36 offset1:38
	v_mov_b32_e32 v11, v222
	s_add_i32 s3, s3, s31
	s_waitcnt lgkmcnt(4)
	v_mfma_f32_32x32x16_bf16 v[64:79], v[6:9], v[196:199], v[64:79]
	ds_read2_b64 v[6:9], v88 offset0:40 offset1:42
	ds_read2_b64 v[88:91], v88 offset0:44 offset1:46
	ds_read2_b64 v[92:95], v104 offset0:64 offset1:66
	ds_read2_b64 v[96:99], v104 offset0:68 offset1:70
	ds_read2_b64 v[100:103], v104 offset0:72 offset1:74
	ds_read2_b64 v[104:107], v104 offset0:76 offset1:78
	ds_read2_b64 v[108:111], v0 offset0:96 offset1:98
	s_cmpk_lt_i32 s3, 0x400
	s_waitcnt lgkmcnt(10)
	v_mfma_f32_32x32x16_bf16 v[64:79], v[12:15], v[192:195], v[64:79]
	ds_read2_b64 v[12:15], v0 offset0:100 offset1:102
	ds_read2_b64 v[112:115], v0 offset0:104 offset1:106
	ds_read2_b64 v[116:119], v0 offset0:108 offset1:110
	v_lshlrev_b32_e32 v0, 1, v225
	s_waitcnt lgkmcnt(0)
	s_barrier
	v_mfma_f32_32x32x16_bf16 v[64:79], v[2:5], v[188:191], v[64:79]
	v_lshl_add_u64 v[2:3], v[122:123], 0, s[6:7]
	v_lshl_add_u64 v[2:3], v[2:3], 0, v[0:1]
	v_add_co_u32_e32 v4, vcc, s55, v2
	s_nop 1
	v_addc_co_u32_e32 v5, vcc, 0, v3, vcc
	global_load_dwordx2 v[122:123], v[4:5], off
	v_lshl_add_u64 v[2:3], v[2:3], 0, s[10:11]
	v_mfma_f32_32x32x16_bf16 v[48:63], v[80:83], v[200:203], v[48:63]
	global_load_dwordx2 v[80:81], v[2:3], off offset:16
	global_load_dwordx2 v[82:83], v[2:3], off offset:32
	v_lshlrev_b32_e32 v4, 2, v11
	v_xor_b32_e32 v4, 0x80, v4
	ds_bpermute_b32 v4, v4, v10
	v_mfma_f32_32x32x16_bf16 v[48:63], v[84:87], v[196:199], v[48:63]
	v_mfma_f32_32x32x16_bf16 v[48:63], v[6:9], v[192:195], v[48:63]
	s_waitcnt lgkmcnt(0)
	v_add_f32_e32 v6, v10, v4
	global_load_dwordx2 v[10:11], v[2:3], off offset:48
	global_load_dwordx2 v[84:85], v[2:3], off offset:64
	global_load_dwordx2 v[86:87], v[2:3], off offset:80
	global_load_dwordx2 v[124:125], v[2:3], off offset:96
	global_load_dwordx2 v[126:127], v[2:3], off offset:112
	global_load_dwordx2 v[128:129], v[2:3], off offset:128
	v_div_scale_f32 v7, s[16:17], v6, v6, 1.0
	v_rcp_f32_e32 v134, v7
	v_mfma_f32_32x32x16_bf16 v[48:63], v[88:91], v[188:191], v[48:63]
	global_load_dwordx2 v[88:89], v[2:3], off offset:144
	global_load_dwordx2 v[90:91], v[2:3], off offset:160
	global_load_dwordx2 v[130:131], v[2:3], off offset:176
	global_load_dwordx2 v[132:133], v[2:3], off offset:192
	global_load_dwordx2 v[8:9], v[2:3], off offset:208
	global_load_dwordx2 v[4:5], v[2:3], off offset:224
	s_nop 0
	global_load_dwordx2 v[2:3], v[2:3], off offset:240
	v_mfma_f32_32x32x16_bf16 v[32:47], v[92:95], v[200:203], v[32:47]
	v_fma_f32 v92, -v7, v134, 1.0
	v_fmac_f32_e32 v134, v92, v134
	v_div_scale_f32 v92, vcc, 1.0, v6, 1.0
	v_mul_f32_e32 v93, v92, v134
	v_fma_f32 v94, -v7, v93, v92
	v_fmac_f32_e32 v93, v94, v134
	v_fma_f32 v7, -v7, v93, v92
	v_mfma_f32_32x32x16_bf16 v[16:31], v[108:111], v[200:203], v[16:31]
	v_div_fmas_f32 v7, v7, v134, v93
	v_div_fixup_f32 v92, v7, v6, 1.0
	v_mul_f32_e32 v64, v64, v92
	v_lshlrev_b64 v[6:7], 12, v[120:121]
	v_mul_f32_e32 v65, v65, v92
	v_lshl_add_u64 v[6:7], s[22:23], 0, v[6:7]
	v_lshl_add_u64 v[6:7], v[6:7], 0, s[6:7]
	v_lshl_add_u64 v[6:7], v[6:7], 0, v[0:1]
	v_mul_f32_e32 v0, v68, v92
	v_mfma_f32_32x32x16_bf16 v[16:31], v[12:15], v[196:199], v[16:31]
	v_mul_f32_e32 v12, v69, v92
	s_waitcnt vmcnt(15)
	v_lshlrev_b32_e32 v93, 16, v122
	v_mul_f32_e32 v64, v64, v93
	v_and_b32_e32 v93, 0xffff0000, v122
	v_mul_f32_e32 v65, v65, v93
	v_cvt_pk_bf16_f32 v244, v64, v65
	v_mul_f32_e32 v65, v66, v92
	v_lshlrev_b32_e32 v66, 16, v123
	v_mul_f32_e32 v65, v65, v66
	v_mul_f32_e32 v66, v67, v92
	v_and_b32_e32 v67, 0xffff0000, v123
	v_mul_f32_e32 v66, v66, v67
	v_cvt_pk_bf16_f32 v245, v65, v66
	v_and_b32_e32 v252, 32, v222
	v_lshrrev_b32_e32 v252, 2, v252
	v_mov_b32_e32 v253, 0
	v_lshl_add_u64 v[252:253], v[6:7], 0, v[252:253]
	s_waitcnt vmcnt(14)
	v_lshlrev_b32_e32 v64, 16, v80
	v_and_b32_e32 v13, 0xffff0000, v80
	v_mul_f32_e32 v0, v0, v64
	v_mul_f32_e32 v12, v12, v13
	v_cvt_pk_bf16_f32 v246, v0, v12
	v_mul_f32_e32 v0, v70, v92
	v_lshlrev_b32_e32 v13, 16, v81
	v_mul_f32_e32 v0, v0, v13
	v_mul_f32_e32 v13, v71, v92
	v_and_b32_e32 v14, 0xffff0000, v81
	v_mul_f32_e32 v13, v13, v14
	v_cvt_pk_bf16_f32 v247, v0, v13
	s_nop 1
	v_permlane32_swap_b32_e32 v244, v246
	v_permlane32_swap_b32_e32 v245, v247
	global_store_dwordx4 v[252:253], v[244:247], off offset:1024
	v_mul_f32_e32 v0, v72, v92
	s_waitcnt vmcnt(14)
	v_lshlrev_b32_e32 v12, 16, v82
	v_mul_f32_e32 v0, v0, v12
	v_mul_f32_e32 v12, v73, v92
	v_and_b32_e32 v13, 0xffff0000, v82
	v_mul_f32_e32 v12, v12, v13
	v_cvt_pk_bf16_f32 v248, v0, v12
	v_mul_f32_e32 v0, v74, v92
	v_lshlrev_b32_e32 v13, 16, v83
	v_mul_f32_e32 v0, v0, v13
	v_mul_f32_e32 v13, v75, v92
	v_and_b32_e32 v14, 0xffff0000, v83
	v_mul_f32_e32 v13, v13, v14
	v_cvt_pk_bf16_f32 v249, v0, v13
	v_mul_f32_e32 v0, v76, v92
	s_waitcnt vmcnt(13)
; __device__ __forceinline__ unsigned cvt_pk_bf16(float lo, float hi) { unsigned r; asm volatile("v_cvt_pk_bf16_f32 %0, %1, %2" : "=v"(r) : "v"(lo), "v"(hi)); return r; }
; __device__ __forceinline__ float bf_lo(unsigned w) { return __uint_as_float(w << 16); }
; __device__ __forceinline__ float bf_hi(unsigned w) { return __uint_as_float(w & 0xffff0000u); }
; __device__ __forceinline__ void unit(LAS unsigned char* lds, int b, int h, int qb, const bf16_t* Q, const bf16_t* Kn, const bf16_t* Kr, const bf16_t* VT, const bf16_t* proj, bf16_t* ymix, int wv) {
;     ...
;     u32x2 gts[4][4];
; #pragma unroll
;     for (int blk = 0; blk < 4; ++blk)
; #pragma unroll
;         for (int g = 0; g < 4; ++g) gts[blk][g] = *(const u32x2*)(proj + tok * NIN + PJ_BG + h * 128 + 32 * blk + 8 * g + 4 * hi);
; #pragma unroll
;     for (int blk = 0; blk < 4; ++blk)
; #pragma unroll
;         for (int g = 0; g < 4; ++g) { const int dv = 32 * blk + 8 * g + 4 * hi; const u32x2 gt = gts[blk][g];
;             u32x2 w; w.x = cvt_pk_bf16(o[blk][4 * g + 0] * inv * bf_lo(gt.x), o[blk][4 * g + 1] * inv * bf_hi(gt.x)); w.y = cvt_pk_bf16(o[blk][4 * g + 2] * inv * bf_lo(gt.y), o[blk][4 * g + 3] * inv * bf_hi(gt.y));
;             *(u32x2*)(ymix + tok * DM + 512 + h * 128 + dv) = w; }
	v_lshlrev_b32_e32 v12, 16, v10
	v_mul_f32_e32 v0, v0, v12
	v_mul_f32_e32 v12, v77, v92
	v_and_b32_e32 v10, 0xffff0000, v10
	v_mul_f32_e32 v10, v12, v10
	v_cvt_pk_bf16_f32 v250, v0, v10
	v_mul_f32_e32 v0, v78, v92
	v_lshlrev_b32_e32 v12, 16, v11
	v_mul_f32_e32 v0, v0, v12
	v_mul_f32_e32 v12, v79, v92
	v_and_b32_e32 v11, 0xffff0000, v11
	v_mul_f32_e32 v11, v12, v11
	v_mfma_f32_32x32x16_bf16 v[32:47], v[96:99], v[196:199], v[32:47]
	v_cvt_pk_bf16_f32 v251, v0, v11
	s_nop 1
	v_permlane32_swap_b32_e32 v248, v250
	v_permlane32_swap_b32_e32 v249, v251
	global_store_dwordx4 v[252:253], v[248:251], off offset:1056
	v_mul_f32_e32 v0, v48, v92
	s_waitcnt vmcnt(13)
	v_lshlrev_b32_e32 v10, 16, v84
	v_mul_f32_e32 v0, v0, v10
	v_mul_f32_e32 v10, v49, v92
	v_and_b32_e32 v11, 0xffff0000, v84
	v_mul_f32_e32 v10, v10, v11
	v_cvt_pk_bf16_f32 v244, v0, v10
	v_mul_f32_e32 v0, v50, v92
	v_lshlrev_b32_e32 v11, 16, v85
	v_mul_f32_e32 v0, v0, v11
	v_mul_f32_e32 v11, v51, v92
	v_and_b32_e32 v12, 0xffff0000, v85
	v_mul_f32_e32 v11, v11, v12
	v_cvt_pk_bf16_f32 v245, v0, v11
	v_mul_f32_e32 v0, v52, v92
	s_waitcnt vmcnt(12)
	v_lshlrev_b32_e32 v10, 16, v86
	v_mul_f32_e32 v0, v0, v10
	v_mul_f32_e32 v10, v53, v92
	v_and_b32_e32 v11, 0xffff0000, v86
	v_mfma_f32_32x32x16_bf16 v[32:47], v[100:103], v[192:195], v[32:47]
	v_mul_f32_e32 v10, v10, v11
	v_cvt_pk_bf16_f32 v246, v0, v10
	v_mul_f32_e32 v0, v54, v92
	v_lshlrev_b32_e32 v11, 16, v87
	v_mul_f32_e32 v0, v0, v11
	v_mul_f32_e32 v11, v55, v92
	v_and_b32_e32 v12, 0xffff0000, v87
	v_mul_f32_e32 v11, v11, v12
	v_cvt_pk_bf16_f32 v247, v0, v11
	s_nop 1
	v_permlane32_swap_b32_e32 v244, v246
	v_permlane32_swap_b32_e32 v245, v247
	global_store_dwordx4 v[252:253], v[244:247], off offset:1088
	v_mul_f32_e32 v0, v56, v92
	s_waitcnt vmcnt(12)
	v_lshlrev_b32_e32 v10, 16, v124
	v_mul_f32_e32 v0, v0, v10
	v_mul_f32_e32 v10, v57, v92
	v_and_b32_e32 v11, 0xffff0000, v124
	v_mul_f32_e32 v10, v10, v11
	v_cvt_pk_bf16_f32 v248, v0, v10
	v_mul_f32_e32 v0, v58, v92
	v_lshlrev_b32_e32 v11, 16, v125
	v_mfma_f32_32x32x16_bf16 v[32:47], v[104:107], v[188:191], v[32:47]
	v_mul_f32_e32 v0, v0, v11
	v_mul_f32_e32 v11, v59, v92
	v_and_b32_e32 v12, 0xffff0000, v125
	v_mul_f32_e32 v11, v11, v12
	v_cvt_pk_bf16_f32 v249, v0, v11
	v_mul_f32_e32 v0, v60, v92
	s_waitcnt vmcnt(11)
	v_lshlrev_b32_e32 v10, 16, v126
	v_mul_f32_e32 v0, v0, v10
	v_mul_f32_e32 v10, v61, v92
	v_and_b32_e32 v11, 0xffff0000, v126
	v_mul_f32_e32 v10, v10, v11
	v_cvt_pk_bf16_f32 v250, v0, v10
	v_mul_f32_e32 v0, v62, v92
	v_lshlrev_b32_e32 v11, 16, v127
	v_mul_f32_e32 v0, v0, v11
	v_mul_f32_e32 v11, v63, v92
	v_and_b32_e32 v12, 0xffff0000, v127
	v_mul_f32_e32 v11, v11, v12
	v_cvt_pk_bf16_f32 v251, v0, v11
	s_nop 1
	v_permlane32_swap_b32_e32 v248, v250
	v_permlane32_swap_b32_e32 v249, v251
	global_store_dwordx4 v[252:253], v[248:251], off offset:1120
	v_mul_f32_e32 v0, v32, v92
	s_waitcnt vmcnt(11)
	v_lshlrev_b32_e32 v10, 16, v128
	v_mul_f32_e32 v0, v0, v10
	v_mul_f32_e32 v10, v33, v92
	v_and_b32_e32 v11, 0xffff0000, v128
	v_mul_f32_e32 v10, v10, v11
	v_cvt_pk_bf16_f32 v244, v0, v10
	v_mul_f32_e32 v0, v34, v92
	v_lshlrev_b32_e32 v11, 16, v129
	v_mul_f32_e32 v0, v0, v11
	v_mul_f32_e32 v11, v35, v92
	v_and_b32_e32 v12, 0xffff0000, v129
	v_mul_f32_e32 v11, v11, v12
	v_cvt_pk_bf16_f32 v245, v0, v11
	v_mul_f32_e32 v0, v36, v92
	s_waitcnt vmcnt(10)
; __device__ __forceinline__ unsigned cvt_pk_bf16(float lo, float hi) { unsigned r; asm volatile("v_cvt_pk_bf16_f32 %0, %1, %2" : "=v"(r) : "v"(lo), "v"(hi)); return r; }
; __device__ __forceinline__ float bf_lo(unsigned w) { return __uint_as_float(w << 16); }
; __device__ __forceinline__ float bf_hi(unsigned w) { return __uint_as_float(w & 0xffff0000u); }
; __device__ __forceinline__ void unit(LAS unsigned char* lds, int b, int h, int qb, const bf16_t* Q, const bf16_t* Kn, const bf16_t* Kr, const bf16_t* VT, const bf16_t* proj, bf16_t* ymix, int wv) {
;     ...
;     u32x2 gts[4][4];
; #pragma unroll
;     for (int blk = 0; blk < 4; ++blk)
; #pragma unroll
;         for (int g = 0; g < 4; ++g) gts[blk][g] = *(const u32x2*)(proj + tok * NIN + PJ_BG + h * 128 + 32 * blk + 8 * g + 4 * hi);
; #pragma unroll
;     for (int blk = 0; blk < 4; ++blk)
; #pragma unroll
;         for (int g = 0; g < 4; ++g) { const int dv = 32 * blk + 8 * g + 4 * hi; const u32x2 gt = gts[blk][g];
;             u32x2 w; w.x = cvt_pk_bf16(o[blk][4 * g + 0] * inv * bf_lo(gt.x), o[blk][4 * g + 1] * inv * bf_hi(gt.x)); w.y = cvt_pk_bf16(o[blk][4 * g + 2] * inv * bf_lo(gt.y), o[blk][4 * g + 3] * inv * bf_hi(gt.y));
;             *(u32x2*)(ymix + tok * DM + 512 + h * 128 + dv) = w; }
	v_lshlrev_b32_e32 v10, 16, v88
	v_mul_f32_e32 v0, v0, v10
	v_mul_f32_e32 v10, v37, v92
	v_and_b32_e32 v11, 0xffff0000, v88
	v_mfma_f32_32x32x16_bf16 v[16:31], v[112:115], v[192:195], v[16:31]
	v_mul_f32_e32 v10, v10, v11
	v_cvt_pk_bf16_f32 v246, v0, v10
	v_mul_f32_e32 v0, v38, v92
	v_lshlrev_b32_e32 v11, 16, v89
	v_mul_f32_e32 v0, v0, v11
	v_mul_f32_e32 v11, v39, v92
	v_and_b32_e32 v12, 0xffff0000, v89
	v_mul_f32_e32 v11, v11, v12
	v_cvt_pk_bf16_f32 v247, v0, v11
	s_nop 1
	v_permlane32_swap_b32_e32 v244, v246
	v_permlane32_swap_b32_e32 v245, v247
	global_store_dwordx4 v[252:253], v[244:247], off offset:1152
	v_mul_f32_e32 v0, v40, v92
	s_waitcnt vmcnt(10)
	v_lshlrev_b32_e32 v10, 16, v90
	v_mul_f32_e32 v0, v0, v10
	v_mul_f32_e32 v10, v41, v92
	v_and_b32_e32 v11, 0xffff0000, v90
	v_mul_f32_e32 v10, v10, v11
	v_cvt_pk_bf16_f32 v248, v0, v10
	v_mul_f32_e32 v0, v42, v92
	v_lshlrev_b32_e32 v11, 16, v91
	v_mfma_f32_32x32x16_bf16 v[16:31], v[116:119], v[188:191], v[16:31]
	v_mul_f32_e32 v0, v0, v11
	v_mul_f32_e32 v11, v43, v92
	v_and_b32_e32 v12, 0xffff0000, v91
	v_mul_f32_e32 v11, v11, v12
	v_cvt_pk_bf16_f32 v249, v0, v11
	v_mul_f32_e32 v0, v44, v92
	s_waitcnt vmcnt(9)
	v_lshlrev_b32_e32 v10, 16, v130
	v_mul_f32_e32 v0, v0, v10
	v_mul_f32_e32 v10, v45, v92
	v_and_b32_e32 v11, 0xffff0000, v130
	v_mul_f32_e32 v10, v10, v11
	v_cvt_pk_bf16_f32 v250, v0, v10
	v_mul_f32_e32 v0, v46, v92
	v_lshlrev_b32_e32 v11, 16, v131
	v_mul_f32_e32 v0, v0, v11
	v_mul_f32_e32 v11, v47, v92
	v_and_b32_e32 v12, 0xffff0000, v131
	v_mul_f32_e32 v11, v11, v12
	v_cvt_pk_bf16_f32 v251, v0, v11
	s_nop 1
	v_permlane32_swap_b32_e32 v248, v250
	v_permlane32_swap_b32_e32 v249, v251
	global_store_dwordx4 v[252:253], v[248:251], off offset:1184
	v_mul_f32_e32 v0, v16, v92
	s_waitcnt vmcnt(9)
	v_lshlrev_b32_e32 v10, 16, v132
	v_mul_f32_e32 v0, v0, v10
	v_mul_f32_e32 v10, v17, v92
	v_and_b32_e32 v11, 0xffff0000, v132
	v_mul_f32_e32 v10, v10, v11
	v_cvt_pk_bf16_f32 v244, v0, v10
	v_mul_f32_e32 v0, v18, v92
	v_lshlrev_b32_e32 v11, 16, v133
	v_mul_f32_e32 v0, v0, v11
	v_mul_f32_e32 v11, v19, v92
	v_and_b32_e32 v12, 0xffff0000, v133
	v_mul_f32_e32 v11, v11, v12
	v_cvt_pk_bf16_f32 v245, v0, v11
	v_mul_f32_e32 v0, v20, v92
	s_waitcnt vmcnt(8)
	v_lshlrev_b32_e32 v10, 16, v8
	v_mul_f32_e32 v0, v0, v10
	v_mul_f32_e32 v10, v21, v92
	v_and_b32_e32 v8, 0xffff0000, v8
	v_mul_f32_e32 v8, v10, v8
	v_cvt_pk_bf16_f32 v246, v0, v8
	v_mul_f32_e32 v0, v22, v92
	v_lshlrev_b32_e32 v10, 16, v9
	v_mul_f32_e32 v0, v0, v10
	v_mul_f32_e32 v10, v23, v92
	v_and_b32_e32 v9, 0xffff0000, v9
	v_mul_f32_e32 v9, v10, v9
	v_cvt_pk_bf16_f32 v247, v0, v9
	s_nop 1
	v_permlane32_swap_b32_e32 v244, v246
	v_permlane32_swap_b32_e32 v245, v247
	global_store_dwordx4 v[252:253], v[244:247], off offset:1216
	v_mul_f32_e32 v0, v24, v92
	s_waitcnt vmcnt(8)
	v_lshlrev_b32_e32 v8, 16, v4
	v_mul_f32_e32 v0, v0, v8
	v_mul_f32_e32 v8, v25, v92
	v_and_b32_e32 v4, 0xffff0000, v4
	v_mul_f32_e32 v4, v8, v4
	v_cvt_pk_bf16_f32 v248, v0, v4
	v_mul_f32_e32 v0, v26, v92
	v_lshlrev_b32_e32 v8, 16, v5
	v_mul_f32_e32 v0, v0, v8
	v_mul_f32_e32 v8, v27, v92
	v_and_b32_e32 v5, 0xffff0000, v5
	v_mul_f32_e32 v5, v8, v5
	v_cvt_pk_bf16_f32 v249, v0, v5
	v_mul_f32_e32 v0, v28, v92
	s_waitcnt vmcnt(7)
	v_lshlrev_b32_e32 v4, 16, v2
	v_mul_f32_e32 v0, v0, v4
	v_mul_f32_e32 v4, v29, v92
	v_and_b32_e32 v2, 0xffff0000, v2
	v_mul_f32_e32 v2, v4, v2
	v_cvt_pk_bf16_f32 v250, v0, v2
	v_mul_f32_e32 v0, v30, v92
	v_lshlrev_b32_e32 v4, 16, v3
	v_mul_f32_e32 v0, v0, v4
	v_mul_f32_e32 v4, v31, v92
	v_and_b32_e32 v3, 0xffff0000, v3
	v_mul_f32_e32 v3, v4, v3
	v_cvt_pk_bf16_f32 v251, v0, v3
	s_nop 1
	v_permlane32_swap_b32_e32 v248, v250
	v_permlane32_swap_b32_e32 v249, v251
	global_store_dwordx4 v[252:253], v[248:251], off offset:1248
	s_cbranch_scc0 .LBB0_1198
